# scan A step loop: waits moved to first consumer (K~/decay at the LDS publish, V fragments at the first state-update MFMA); prologue drains once before the loop
# speedup vs baseline: 1.0007x; 1.0007x over previous
; template <bool OUT>
; DI void scan_segment(const P& p, f32x16 (&S)[4], int b, int hd, int dir, int s0, int s1, float& dp0, float& dp1) {
;     ...
;   fetch(s0, IC<0>{}, true); fetch(min(s0 + 1, s1 - 1), IC<1>{}, true);
; #pragma unroll 1
;   for (int step = s0; step < s1; step += 2) {
;     body(step, IC<0>{});
;     if (step + 1 < s1) body(step + 1, IC<1>{});
;   }
; DI void gla_scan_A(const P& p, int u) {
;     ...
;   f32x16 S[4];
; #pragma unroll
;   for (int a = 0; a < 4; ++a)
; #pragma unroll
;     for (int i = 0; i < 16; ++i) S[a][i] = 0.f;
;   float dp0 = 1.f, dp1 = 1.f;
.LBB0_301:
	s_lshl_b64 s[16:17], s[14:15], 1
	s_or_b64 s[16:17], s[16:17], s[10:11]
	s_lshl_b64 s[14:15], s[14:15], 15
	s_add_i32 s29, s33, 16
	s_add_i32 s30, s33, 17
	s_lshl_b64 s[18:19], s[16:17], 9
	v_lshl_add_u64 v[4:5], v[124:125], 0, s[14:15]
	s_lshl_b64 s[14:15], s[16:17], 14
	s_add_u32 s14, s24, s14
	v_lshl_add_u64 v[2:3], v[118:119], 0, s[18:19]
	s_addc_u32 s15, s25, s15
	v_mov_b32_e32 v131, v115
	global_load_dword v165, v[2:3], off offset:256
	global_load_dwordx4 v[94:97], v[4:5], off
	global_load_dword v168, v[2:3], off
	global_load_dwordx4 v[86:89], v[4:5], off offset:64
	global_load_dwordx4 v[90:93], v[4:5], off offset:32
	v_lshl_add_u64 v[2:3], s[14:15], 0, v[130:131]
	v_mov_b32_e32 v127, v115
	v_lshl_add_u64 v[2:3], v[2:3], 0, v[126:127]
	v_mov_b32_e32 v129, v115
	v_lshl_add_u64 v[2:3], v[2:3], 0, v[128:129]
	global_load_dwordx4 v[82:85], v[4:5], off offset:96
	global_load_dwordx4 v[106:109], v[2:3], off
	v_lshl_add_u64 v[2:3], s[14:15], 0, v[114:115]
	v_lshl_add_u64 v[2:3], v[2:3], 0, v[126:127]
	v_lshl_add_u64 v[2:3], v[2:3], 0, v[128:129]
	global_load_dwordx4 v[110:113], v[2:3], off
	s_cmp_eq_u32 s10, 0
	s_cselect_b64 s[14:15], -1, 0
	s_and_b64 s[16:17], s[14:15], exec
	s_cselect_b32 s16, 3, 0
	s_or_b32 s16, s9, s16
	s_ashr_i32 s17, s16, 31
	s_lshl_b64 s[16:17], s[16:17], 2
	v_mov_b32_e32 v16, v115
	v_mov_b32_e32 v17, v115
	s_add_u32 s16, s16, s12
	v_mov_b32_e32 v2, v115
	v_mov_b32_e32 v3, v115
	v_mov_b32_e32 v4, v115
	v_mov_b32_e32 v5, v115
	v_mov_b32_e32 v6, v115
	v_mov_b32_e32 v7, v115
	v_mov_b32_e32 v8, v115
	v_mov_b32_e32 v9, v115
	v_mov_b32_e32 v10, v115
	v_mov_b32_e32 v11, v115
	v_mov_b32_e32 v12, v115
	v_mov_b32_e32 v13, v115
	v_mov_b32_e32 v14, v115
	v_mov_b32_e32 v15, v115
	v_mov_b64_e32 v[32:33], v[16:17]
	v_mov_b64_e32 v[48:49], v[16:17]
	v_mov_b64_e32 v[64:65], v[16:17]
	v_or_b32_e32 v136, 4, v132
	v_or_b32_e32 v137, 8, v132
	v_or_b32_e32 v138, 12, v132
	v_or_b32_e32 v139, 32, v132
	v_or_b32_e32 v140, 36, v132
	v_or_b32_e32 v141, 40, v132
	v_or_b32_e32 v142, 44, v132
	v_or_b32_e32 v143, 64, v132
	v_or_b32_e32 v144, 0x44, v132
	v_or_b32_e32 v145, 0x48, v132
	v_or_b32_e32 v146, 0x4c, v132
	v_or_b32_e32 v147, 0x60, v132
	v_or_b32_e32 v148, 0x64, v132
	v_or_b32_e32 v149, 0x68, v132
	v_or_b32_e32 v150, 0x6c, v132
	v_or_b32_e32 v151, 0x80, v132
	v_or_b32_e32 v152, 0x84, v132
	v_or_b32_e32 v153, 0x88, v132
	v_or_b32_e32 v154, 0x8c, v132
	v_or_b32_e32 v155, 0xa0, v132
	v_or_b32_e32 v156, 0xa4, v132
	v_or_b32_e32 v157, 0xa8, v132
	v_or_b32_e32 v158, 0xac, v132
	v_or_b32_e32 v159, 0xc0, v132
	v_or_b32_e32 v160, 0xc4, v132
	v_or_b32_e32 v161, 0xc8, v132
	v_or_b32_e32 v162, 0xcc, v132
	v_or_b32_e32 v163, 0xe0, v132
	v_or_b32_e32 v164, 0xe4, v132
	v_or_b32_e32 v166, 0xe8, v132
	v_or_b32_e32 v167, 0xec, v132
	s_addc_u32 s17, s17, s13
	v_mov_b32_e32 v134, 1.0
	v_mov_b64_e32 v[30:31], v[14:15]
	v_mov_b64_e32 v[28:29], v[12:13]
	v_mov_b64_e32 v[26:27], v[10:11]
	v_mov_b64_e32 v[24:25], v[8:9]
	v_mov_b64_e32 v[22:23], v[6:7]
	v_mov_b64_e32 v[20:21], v[4:5]
	v_mov_b64_e32 v[18:19], v[2:3]
	v_mov_b64_e32 v[46:47], v[14:15]
	v_mov_b64_e32 v[44:45], v[12:13]
	v_mov_b64_e32 v[42:43], v[10:11]
	v_mov_b64_e32 v[40:41], v[8:9]
	v_mov_b64_e32 v[38:39], v[6:7]
	v_mov_b64_e32 v[36:37], v[4:5]
	v_mov_b64_e32 v[34:35], v[2:3]
	v_mov_b64_e32 v[62:63], v[14:15]
	v_mov_b64_e32 v[60:61], v[12:13]
	v_mov_b64_e32 v[58:59], v[10:11]
	v_mov_b64_e32 v[56:57], v[8:9]
	v_mov_b64_e32 v[54:55], v[6:7]
	v_mov_b64_e32 v[52:53], v[4:5]
	v_mov_b64_e32 v[50:51], v[2:3]
	v_mov_b32_e32 v135, 1.0
	s_waitcnt vmcnt(0)
.LBB0_302:
	s_add_i32 s31, s33, 2
	s_min_i32 s34, s31, s29
	s_cmp_gt_u32 s34, 3
	s_cselect_b64 s[18:19], -1, 0
	s_mov_b64 s[22:23], -1
	s_and_b64 vcc, exec, s[18:19]
	s_waitcnt vmcnt(12)
	ds_write_b128 v133, v[98:101] offset:16384
	ds_write_b128 v133, v[102:105] offset:17408
	s_waitcnt lgkmcnt(0)
	s_barrier
	s_cbranch_vccz .LBB0_304
	s_add_i32 s22, s34, -4
	s_sub_i32 s23, 0x103, s34
	s_and_b64 s[20:21], s[14:15], exec
	s_cselect_b32 s20, s22, s23
	s_add_i32 s20, s20, s28
	s_mov_b64 s[22:23], 0

; #define MFMA32(a, b, c) __builtin_amdgcn_mfma_f32_32x32x16_bf16((a), (b), (c), 0, 0, 0)
; DI void scan_decay(f32x16 (&S)[4], float d0, float d1, int h2) {
; #pragma unroll
;   for (int a = 0; a < 4; ++a)
; #pragma unroll
;     for (int i = 0; i < 16; ++i) { const int src = 32 * (a & 1) + (i & 3) + 8 * (i >> 2) + 4 * h2; S[a][i] *= __shfl((a < 2) ? d0 : d1, src, 64); }
; }
; template <bool OUT>
; DI void scan_segment(const P& p, f32x16 (&S)[4], int b, int hd, int dir, int s0, int s1, float& dp0, float& dp1) {
;     ...
;     if (!OUT || step + 1 < s1) {
;       scan_decay(S, c0, c1, h2);
;       if (!OUT && wid == 0) { dp0 *= c0; dp1 *= c1; }
; #pragma unroll
;       for (int s = 0; s < 4; ++s)
; #pragma unroll
;         for (int a = 0; a < 4; ++a) { bf16x8 ka = *(const bf16x8*)(ib + (16 + s * 4 + a) * 1024 + lane * 16); S[a] = MFMA32(ka, vb[Q][s], S[a]); }
.LBB0_306:
	ds_bpermute_b32 v98, v132, v170
	ds_bpermute_b32 v99, v136, v170
	ds_bpermute_b32 v100, v137, v170
	ds_bpermute_b32 v101, v138, v170
	ds_bpermute_b32 v102, v139, v170
	ds_bpermute_b32 v103, v140, v170
	ds_bpermute_b32 v104, v141, v170
	ds_bpermute_b32 v105, v142, v170
	s_waitcnt lgkmcnt(4)
	v_pk_mul_f32 v[52:53], v[52:53], v[100:101]
	v_pk_mul_f32 v[50:51], v[50:51], v[98:99]
	s_waitcnt lgkmcnt(2)
	v_pk_mul_f32 v[54:55], v[54:55], v[102:103]
	ds_bpermute_b32 v98, v151, v170
	s_waitcnt lgkmcnt(1)
	v_pk_mul_f32 v[56:57], v[56:57], v[104:105]
	ds_bpermute_b32 v99, v152, v170
	ds_bpermute_b32 v100, v153, v170
	ds_bpermute_b32 v101, v154, v170
	ds_bpermute_b32 v102, v155, v170
	ds_bpermute_b32 v103, v156, v170
	ds_bpermute_b32 v104, v157, v170
	ds_bpermute_b32 v105, v158, v170
	s_waitcnt lgkmcnt(4)
	v_pk_mul_f32 v[36:37], v[36:37], v[100:101]
	v_pk_mul_f32 v[34:35], v[34:35], v[98:99]
	s_waitcnt lgkmcnt(2)
	v_pk_mul_f32 v[38:39], v[38:39], v[102:103]
	ds_bpermute_b32 v102, v132, v169
	s_waitcnt lgkmcnt(1)
	v_pk_mul_f32 v[40:41], v[40:41], v[104:105]
	ds_bpermute_b32 v103, v136, v169
	ds_bpermute_b32 v104, v137, v169
	ds_bpermute_b32 v105, v138, v169
	ds_bpermute_b32 v98, v139, v169
	ds_bpermute_b32 v99, v140, v169
	ds_bpermute_b32 v100, v141, v169
	ds_bpermute_b32 v101, v142, v169
	ds_bpermute_b32 v172, v143, v170
	ds_bpermute_b32 v174, v145, v170
	ds_bpermute_b32 v176, v147, v170
	ds_bpermute_b32 v178, v149, v170
	ds_bpermute_b32 v179, v150, v170
	ds_bpermute_b32 v177, v148, v170
	ds_bpermute_b32 v175, v146, v170
	ds_bpermute_b32 v173, v144, v170
	v_add_u32_e32 v171, 0, v1
	s_waitcnt lgkmcnt(8)
	v_pk_mul_f32 v[24:25], v[24:25], v[100:101]
	v_pk_mul_f32 v[22:23], v[22:23], v[98:99]
	ds_read_b128 v[98:101], v171 offset:16384
	v_pk_mul_f32 v[20:21], v[20:21], v[104:105]
	v_pk_mul_f32 v[18:19], v[18:19], v[102:103]
	ds_read_b128 v[102:105], v171 offset:17408
	s_waitcnt lgkmcnt(5)
	v_pk_mul_f32 v[64:65], v[64:65], v[178:179]
	s_waitcnt lgkmcnt(4)
	v_pk_mul_f32 v[62:63], v[62:63], v[176:177]
	s_waitcnt lgkmcnt(3)
	v_pk_mul_f32 v[60:61], v[60:61], v[174:175]
	s_waitcnt lgkmcnt(2)
	v_pk_mul_f32 v[58:59], v[58:59], v[172:173]
	ds_bpermute_b32 v172, v159, v170
	ds_bpermute_b32 v174, v161, v170
	ds_bpermute_b32 v176, v163, v170
	ds_bpermute_b32 v178, v166, v170
	ds_bpermute_b32 v179, v167, v170
	ds_bpermute_b32 v177, v164, v170
	ds_bpermute_b32 v175, v162, v170
	ds_bpermute_b32 v173, v160, v170
	s_waitcnt lgkmcnt(9)
	s_waitcnt vmcnt(8)
	v_mfma_f32_32x32x16_bf16 v[50:65], v[98:101], v[78:81], v[50:65]
	s_waitcnt lgkmcnt(3)
	v_mul_f32_e64 v48, v48, v178
	v_mul_f32_e64 v49, v49, v179
	s_waitcnt lgkmcnt(2)
	v_mul_f32_e64 v46, v46, v176
	v_mul_f32_e64 v47, v47, v177
	s_waitcnt lgkmcnt(1)
	v_pk_mul_f32 v[44:45], v[44:45], v[174:175]
	s_waitcnt lgkmcnt(0)
	v_pk_mul_f32 v[42:43], v[42:43], v[172:173]
	ds_bpermute_b32 v172, v143, v169
	ds_bpermute_b32 v174, v145, v169
	ds_bpermute_b32 v176, v147, v169
	ds_bpermute_b32 v178, v149, v169
	ds_bpermute_b32 v179, v150, v169
	ds_bpermute_b32 v177, v148, v169
	ds_bpermute_b32 v175, v146, v169
	ds_bpermute_b32 v173, v144, v169
	ds_read_b128 v[98:101], v171 offset:18432
	v_mfma_f32_32x32x16_bf16 v[34:49], v[102:105], v[78:81], v[34:49]
	ds_read_b128 v[102:105], v171 offset:19456
	s_waitcnt lgkmcnt(5)
	v_mul_f32_e64 v32, v32, v178
	v_mul_f32_e64 v33, v33, v179
	s_waitcnt lgkmcnt(4)
	v_pk_mul_f32 v[30:31], v[30:31], v[176:177]
	s_waitcnt lgkmcnt(3)
	v_pk_mul_f32 v[28:29], v[28:29], v[174:175]
	s_waitcnt lgkmcnt(2)
; #define MFMA32(a, b, c) __builtin_amdgcn_mfma_f32_32x32x16_bf16((a), (b), (c), 0, 0, 0)
; template <bool OUT>
; DI void scan_segment(const P& p, f32x16 (&S)[4], int b, int hd, int dir, int s0, int s1, float& dp0, float& dp1) {
;     ...
;   auto fetch = [&](int step, auto PP, bool with_v) {
;     constexpr int Q = decltype(PP)::value;
;     bool isctx; int n; size_t unit; scan_step_addr(p, b, hd, dir, step, isctx, n, unit);
;     const bf16_t* qi = QI + (unit * 2 + dir) * 8192; const bf16_t* kst = KST + (unit * 2 + dir) * 8192; const float* dd = DD + (unit * 2 + dir) * 128;
;     const bf16_t* vt = VT + unit * 16384 + (size_t)(wid * 32) * 64;
; #pragma unroll
;     for (int e = 0; e < 2; ++e) { const int f = 2 * wid + e;
;       if (OUT) { const int m = f >> 3, a = (f >> 1) & 3, s = f & 1; kq[Q][e] = *(const bf16x8*)(qi + (32 * m + r) * 128 + a * 32 + s * 16 + h2 * 8); }
;       { const int s = f >> 2, a = f & 3; kk[Q][e] = *(const bf16x8*)(kst + (32 * a + r) * 64 + s * 16 + h2 * 8); } }
;     if (with_v) {
; #pragma unroll
;       for (int s = 0; s < 4; ++s) vb[Q][s] = *(const bf16x8*)(vt + r * 64 + s * 16 + h2 * 8); }
;     d0[Q] = dd[lane]; d1[Q] = dd[64 + lane];
;   };
;     ...
;     if (!OUT || step + 1 < s1) {
;       scan_decay(S, c0, c1, h2);
;       if (!OUT && wid == 0) { dp0 *= c0; dp1 *= c1; }
; #pragma unroll
;       for (int s = 0; s < 4; ++s)
; #pragma unroll
;         for (int a = 0; a < 4; ++a) { bf16x8 ka = *(const bf16x8*)(ib + (16 + s * 4 + a) * 1024 + lane * 16); S[a] = MFMA32(ka, vb[Q][s], S[a]); }
;     }
;     fetch_v(min(step + 2, s1 - 1), PP);
	v_pk_mul_f32 v[26:27], v[26:27], v[172:173]
	ds_bpermute_b32 v172, v151, v169
	ds_bpermute_b32 v173, v152, v169
	ds_bpermute_b32 v174, v153, v169
	ds_bpermute_b32 v175, v154, v169
	ds_bpermute_b32 v176, v155, v169
	ds_bpermute_b32 v177, v156, v169
	ds_bpermute_b32 v178, v157, v169
	ds_bpermute_b32 v179, v158, v169
	ds_bpermute_b32 v180, v159, v169
	ds_bpermute_b32 v181, v160, v169
	ds_bpermute_b32 v182, v166, v169
	ds_bpermute_b32 v183, v167, v169
	ds_bpermute_b32 v184, v161, v169
	ds_bpermute_b32 v186, v163, v169
	ds_bpermute_b32 v187, v164, v169
	ds_bpermute_b32 v185, v162, v169
	s_waitcnt lgkmcnt(4)
	v_pk_mul_f32 v[16:17], v[16:17], v[182:183]
	v_pk_mul_f32 v[10:11], v[10:11], v[180:181]
	v_pk_mul_f32 v[8:9], v[8:9], v[178:179]
	s_waitcnt lgkmcnt(1)
	v_pk_mul_f32 v[14:15], v[14:15], v[186:187]
	s_waitcnt lgkmcnt(0)
	v_pk_mul_f32 v[12:13], v[12:13], v[184:185]
	v_pk_mul_f32 v[6:7], v[6:7], v[176:177]
	v_pk_mul_f32 v[4:5], v[4:5], v[174:175]
	v_pk_mul_f32 v[2:3], v[2:3], v[172:173]
	v_mfma_f32_32x32x16_bf16 v[18:33], v[98:101], v[78:81], v[18:33]
	s_ashr_i32 s21, s20, 31
	s_lshl_b64 s[20:21], s[20:21], 3
	s_lshl_b64 s[22:23], s[22:23], 1
	s_add_u32 s20, s20, s22
	s_addc_u32 s21, s21, s23
	s_or_b64 s[20:21], s[20:21], s[10:11]
	s_lshl_b64 s[22:23], s[20:21], 14
	v_mfma_f32_32x32x16_bf16 v[2:17], v[102:105], v[78:81], v[2:17]
	ds_read_b128 v[78:81], v171 offset:20480
	ds_read_b128 v[98:101], v171 offset:21504
	s_add_u32 s22, s24, s22
	s_addc_u32 s23, s25, s23
	v_mov_b32_e32 v127, v115
	v_mov_b32_e32 v131, v115
	v_mov_b32_e32 v129, v115
	s_lshl_b64 s[20:21], s[20:21], 9
	s_waitcnt lgkmcnt(1)
	v_mfma_f32_32x32x16_bf16 v[50:65], v[78:81], v[74:77], v[50:65]
	s_and_b64 vcc, exec, s[18:19]
	s_waitcnt lgkmcnt(0)
	v_mfma_f32_32x32x16_bf16 v[34:49], v[98:101], v[74:77], v[34:49]
	ds_read_b128 v[78:81], v171 offset:22528
	ds_read_b128 v[98:101], v171 offset:23552
	s_waitcnt lgkmcnt(1)
	v_mfma_f32_32x32x16_bf16 v[18:33], v[78:81], v[74:77], v[18:33]
	s_waitcnt lgkmcnt(0)
	v_mfma_f32_32x32x16_bf16 v[2:17], v[98:101], v[74:77], v[2:17]
	ds_read_b128 v[74:77], v171 offset:24576
	ds_read_b128 v[78:81], v171 offset:25600
	s_waitcnt lgkmcnt(1)
	v_mfma_f32_32x32x16_bf16 v[50:65], v[74:77], v[70:73], v[50:65]
	s_waitcnt lgkmcnt(0)
	v_mfma_f32_32x32x16_bf16 v[34:49], v[78:81], v[70:73], v[34:49]
	ds_read_b128 v[74:77], v171 offset:26624
	ds_read_b128 v[78:81], v171 offset:27648
	s_waitcnt lgkmcnt(1)
	v_mfma_f32_32x32x16_bf16 v[18:33], v[74:77], v[70:73], v[18:33]
	ds_read_b128 v[74:77], v171 offset:28672
	s_waitcnt lgkmcnt(1)
	v_mfma_f32_32x32x16_bf16 v[2:17], v[78:81], v[70:73], v[2:17]
	ds_read_b128 v[70:73], v171 offset:29696
	v_lshl_add_u64 v[78:79], s[22:23], 0, v[114:115]
	v_lshl_add_u64 v[80:81], s[22:23], 0, v[130:131]
	s_waitcnt lgkmcnt(1)
	v_mfma_f32_32x32x16_bf16 v[50:65], v[74:77], v[66:69], v[50:65]
	v_lshl_add_u64 v[74:75], v[78:79], 0, v[126:127]
	v_lshl_add_u64 v[78:79], v[74:75], 0, v[128:129]
	ds_read_b128 v[74:77], v171 offset:30720
	s_waitcnt lgkmcnt(1)
	v_mfma_f32_32x32x16_bf16 v[34:49], v[70:73], v[66:69], v[34:49]
	v_lshl_add_u64 v[70:71], v[80:81], 0, v[126:127]
	v_lshl_add_u64 v[70:71], v[70:71], 0, v[128:129]
	global_load_dwordx4 v[98:101], v[78:79], off
	global_load_dwordx4 v[102:105], v[70:71], off
	v_lshl_add_u64 v[78:79], v[118:119], 0, s[20:21]
	ds_read_b128 v[70:73], v171 offset:31744
	global_load_dword v172, v[78:79], off
	global_load_dword v173, v[78:79], off offset:256
	s_mov_b64 s[20:21], -1
	s_waitcnt lgkmcnt(1)
	v_mfma_f32_32x32x16_bf16 v[18:33], v[74:77], v[66:69], v[18:33]
	s_waitcnt lgkmcnt(0)
	v_mfma_f32_32x32x16_bf16 v[2:17], v[70:73], v[66:69], v[2:17]
	s_cbranch_vccz .LBB0_308
	s_add_i32 s20, s34, -4
	s_sub_i32 s21, 0x103, s34
	s_and_b64 s[18:19], s[14:15], exec
	s_cselect_b32 s18, s20, s21
	s_add_i32 s18, s18, s28
	s_mov_b64 s[20:21], 0

; DI void scan_decay(f32x16 (&S)[4], float d0, float d1, int h2) {
; #pragma unroll
;   for (int a = 0; a < 4; ++a)
; #pragma unroll
;     for (int i = 0; i < 16; ++i) { const int src = 32 * (a & 1) + (i & 3) + 8 * (i >> 2) + 4 * h2; S[a][i] *= __shfl((a < 2) ? d0 : d1, src, 64); }
; }
; template <bool OUT>
; DI void scan_segment(const P& p, f32x16 (&S)[4], int b, int hd, int dir, int s0, int s1, float& dp0, float& dp1) {
;     ...
;     d0[Q] = dd[lane]; d1[Q] = dd[64 + lane];
;   };
;   auto fetch_v = [&](int step, auto PP) {
;     constexpr int Q = decltype(PP)::value;
;     bool isctx; int n; size_t unit; scan_step_addr(p, b, hd, dir, step, isctx, n, unit);
;     const bf16_t* vt = VT + unit * 16384 + (size_t)(wid * 32) * 64;
; #pragma unroll
;     for (int s = 0; s < 4; ++s) vb[Q][s] = *(const bf16x8*)(vt + r * 64 + s * 16 + h2 * 8);
;   };
;   auto body = [&](int step, auto PP) {
;     constexpr int Q = decltype(PP)::value;
;     char* ib = img + Q * 32768;
; #pragma unroll
;     for (int e = 0; e < 2; ++e) { const int f = 2 * wid + e;
;       if (OUT) *(bf16x8*)(ib + f * 1024 + lane * 16) = kq[Q][e];
;       *(bf16x8*)(ib + (16 + f) * 1024 + lane * 16) = kk[Q][e]; }
;     const float c0 = d0[Q], c1 = d1[Q];
;     bool isctx; int n; size_t unit; scan_step_addr(p, b, hd, dir, step, isctx, n, unit);
;     __syncthreads();
;     fetch(min(step + 2, s1 - 1), PP, false);
;     if (OUT && !isctx) {
;       f32x16 o0, o1;
; #pragma unroll
;       for (int i = 0; i < 16; ++i) { o0[i] = 0.f; o1[i] = 0.f; }
; #pragma unroll
;       for (int a = 0; a < 4; ++a)
; #pragma unroll
;         for (int s = 0; s < 2; ++s) { bf16x8 sb = pack8(S[a], s);
;           bf16x8 q0 = *(const bf16x8*)(ib + (a * 2 + s) * 1024 + lane * 16), q1 = *(const bf16x8*)(ib + (8 + a * 2 + s) * 1024 + lane * 16);
;           o0 = MFMA32(q0, sb, o0); o1 = MFMA32(q1, sb, o1); }
;       const int tl = otid(), ro = tl & 31, ho = (tl >> 5) & 1;
;       bf16_t* ob = OFB + (size_t)dir * T * 1024 + ((size_t)b * 16384 + (size_t)n * 64 + 4 * ho) * 1024 + hd * 256 + wid * 32 + ro;
; #pragma unroll
;       for (int i = 0; i < 16; ++i) { const int row = (i & 3) + 8 * (i >> 2); ob[(size_t)row * 1024] = f2bf(o0[i]); ob[(size_t)(32 + row) * 1024] = f2bf(o1[i]); }
;     }
;     if (!OUT || step + 1 < s1) {
;       scan_decay(S, c0, c1, h2);
;       if (!OUT && wid == 0) { dp0 *= c0; dp1 *= c1; }
; #pragma unroll
.LBB0_310:
	s_ashr_i32 s19, s18, 31
	s_lshl_b64 s[18:19], s[18:19], 17
	s_lshl_b64 s[20:21], s[20:21], 15
	v_lshl_add_u64 v[66:67], v[116:117], 0, s[18:19]
	v_lshl_add_u64 v[66:67], v[66:67], 0, s[20:21]
	v_mov_b32_e32 v129, v115
	v_lshl_add_u64 v[66:67], v[66:67], 0, v[128:129]
	global_load_dwordx4 v[78:81], v[66:67], off
	global_load_dwordx4 v[74:77], v[66:67], off offset:32
	global_load_dwordx4 v[70:73], v[66:67], off offset:64
	s_nop 0
	global_load_dwordx4 v[66:69], v[66:67], off offset:96
	v_mul_f32_e32 v170, v134, v170
	s_cmp_ge_u32 s33, s29
	v_mul_f32_e32 v169, v135, v169
	s_cbranch_scc1 .LBB0_316
	s_add_i32 s18, s33, 3
	s_min_i32 s22, s18, s29
	s_cmp_gt_u32 s22, 3
	s_cselect_b64 s[18:19], -1, 0
	s_cmp_lt_u32 s22, 4
	s_mov_b64 s[20:21], s[16:17]
	s_waitcnt vmcnt(12)
	ds_write_b128 v133, v[110:113] offset:49152
	ds_write_b128 v133, v[106:109] offset:50176
	s_waitcnt lgkmcnt(0)
	s_barrier
	s_cbranch_scc1 .LBB0_313
	s_add_i32 s23, s22, -4
	s_sub_i32 s33, 0x103, s22
	s_and_b64 s[20:21], s[14:15], exec
	s_cselect_b32 s20, s23, s33
	s_add_i32 s20, s20, s28
	s_ashr_i32 s21, s20, 31
	s_lshl_b64 s[20:21], s[20:21], 2
	s_or_b64 s[20:21], s[20:21], s[6:7]
.LBB0_313:
	s_lshl_b64 s[90:91], s[20:21], 1
	s_or_b64 s[90:91], s[90:91], s[10:11]
	s_lshl_b64 s[90:91], s[90:91], 9
	v_lshl_add_u64 v[192:193], v[118:119], 0, s[90:91]
	global_load_dword v190, v[192:193], off
	global_load_dword v191, v[192:193], off offset:256
	ds_bpermute_b32 v106, v132, v168
	ds_bpermute_b32 v107, v136, v168
	ds_bpermute_b32 v108, v137, v168
	ds_bpermute_b32 v109, v138, v168
	ds_bpermute_b32 v110, v139, v168
	ds_bpermute_b32 v111, v140, v168
	ds_bpermute_b32 v112, v141, v168
	ds_bpermute_b32 v113, v142, v168
	s_waitcnt lgkmcnt(4)
	v_pk_mul_f32 v[52:53], v[52:53], v[108:109]
	v_pk_mul_f32 v[50:51], v[50:51], v[106:107]
	s_waitcnt lgkmcnt(2)
	v_pk_mul_f32 v[54:55], v[54:55], v[110:111]
	ds_bpermute_b32 v106, v151, v168
	s_waitcnt lgkmcnt(1)
	v_pk_mul_f32 v[56:57], v[56:57], v[112:113]
	ds_bpermute_b32 v107, v152, v168
	ds_bpermute_b32 v108, v153, v168
	ds_bpermute_b32 v109, v154, v168
	ds_bpermute_b32 v110, v155, v168
	ds_bpermute_b32 v111, v156, v168
	ds_bpermute_b32 v112, v157, v168
	ds_bpermute_b32 v113, v158, v168
	s_waitcnt lgkmcnt(4)
	v_pk_mul_f32 v[36:37], v[36:37], v[108:109]
	v_pk_mul_f32 v[34:35], v[34:35], v[106:107]
	s_waitcnt lgkmcnt(2)
	v_pk_mul_f32 v[38:39], v[38:39], v[110:111]
	ds_bpermute_b32 v110, v132, v165
	s_waitcnt lgkmcnt(1)
	v_pk_mul_f32 v[40:41], v[40:41], v[112:113]
	ds_bpermute_b32 v111, v136, v165
	ds_bpermute_b32 v112, v137, v165
	ds_bpermute_b32 v113, v138, v165
	ds_bpermute_b32 v106, v139, v165
	ds_bpermute_b32 v107, v140, v165
	ds_bpermute_b32 v108, v141, v165
	ds_bpermute_b32 v109, v142, v165
	ds_bpermute_b32 v174, v143, v168
	ds_bpermute_b32 v176, v145, v168
	ds_bpermute_b32 v178, v147, v168
	ds_bpermute_b32 v180, v149, v168
	ds_bpermute_b32 v181, v150, v168
	ds_bpermute_b32 v179, v148, v168
	ds_bpermute_b32 v177, v146, v168
	ds_bpermute_b32 v175, v144, v168
	s_waitcnt lgkmcnt(8)
	v_pk_mul_f32 v[24:25], v[24:25], v[108:109]
	v_pk_mul_f32 v[22:23], v[22:23], v[106:107]
	ds_read_b128 v[106:109], v171 offset:49152
	v_pk_mul_f32 v[20:21], v[20:21], v[112:113]
	v_pk_mul_f32 v[18:19], v[18:19], v[110:111]
	ds_read_b128 v[110:113], v171 offset:50176
	s_waitcnt lgkmcnt(5)
	v_pk_mul_f32 v[64:65], v[64:65], v[180:181]
	s_waitcnt lgkmcnt(4)
	v_pk_mul_f32 v[62:63], v[62:63], v[178:179]
	s_waitcnt lgkmcnt(3)
	v_pk_mul_f32 v[60:61], v[60:61], v[176:177]
	s_waitcnt lgkmcnt(2)
	v_pk_mul_f32 v[58:59], v[58:59], v[174:175]
	ds_bpermute_b32 v174, v159, v168
	ds_bpermute_b32 v176, v161, v168
	ds_bpermute_b32 v178, v163, v168
	ds_bpermute_b32 v180, v166, v168
	ds_bpermute_b32 v181, v167, v168
	ds_bpermute_b32 v179, v164, v168
	ds_bpermute_b32 v177, v162, v168
	ds_bpermute_b32 v175, v160, v168
	s_waitcnt lgkmcnt(9)
	s_waitcnt vmcnt(10)
	v_mfma_f32_32x32x16_bf16 v[50:65], v[106:109], v[94:97], v[50:65]
	s_waitcnt lgkmcnt(3)
	v_mul_f32_e64 v48, v48, v180
	v_mul_f32_e64 v49, v49, v181
	s_waitcnt lgkmcnt(2)
	v_mul_f32_e64 v46, v46, v178
	v_mul_f32_e64 v47, v47, v179
	s_waitcnt lgkmcnt(1)
	v_pk_mul_f32 v[44:45], v[44:45], v[176:177]
	s_waitcnt lgkmcnt(0)
; #define MFMA32(a, b, c) __builtin_amdgcn_mfma_f32_32x32x16_bf16((a), (b), (c), 0, 0, 0)
; template <bool OUT>
; DI void scan_segment(const P& p, f32x16 (&S)[4], int b, int hd, int dir, int s0, int s1, float& dp0, float& dp1) {
;     ...
;   auto fetch = [&](int step, auto PP, bool with_v) {
;     constexpr int Q = decltype(PP)::value;
;     bool isctx; int n; size_t unit; scan_step_addr(p, b, hd, dir, step, isctx, n, unit);
;     const bf16_t* qi = QI + (unit * 2 + dir) * 8192; const bf16_t* kst = KST + (unit * 2 + dir) * 8192; const float* dd = DD + (unit * 2 + dir) * 128;
;     const bf16_t* vt = VT + unit * 16384 + (size_t)(wid * 32) * 64;
; #pragma unroll
;     for (int e = 0; e < 2; ++e) { const int f = 2 * wid + e;
;       if (OUT) { const int m = f >> 3, a = (f >> 1) & 3, s = f & 1; kq[Q][e] = *(const bf16x8*)(qi + (32 * m + r) * 128 + a * 32 + s * 16 + h2 * 8); }
;       { const int s = f >> 2, a = f & 3; kk[Q][e] = *(const bf16x8*)(kst + (32 * a + r) * 64 + s * 16 + h2 * 8); } }
;     if (with_v) {
; #pragma unroll
;       for (int s = 0; s < 4; ++s) vb[Q][s] = *(const bf16x8*)(vt + r * 64 + s * 16 + h2 * 8); }
;     d0[Q] = dd[lane]; d1[Q] = dd[64 + lane];
;   };
;     ...
;     if (!OUT || step + 1 < s1) {
;       scan_decay(S, c0, c1, h2);
;       if (!OUT && wid == 0) { dp0 *= c0; dp1 *= c1; }
; #pragma unroll
;       for (int s = 0; s < 4; ++s)
; #pragma unroll
;         for (int a = 0; a < 4; ++a) { bf16x8 ka = *(const bf16x8*)(ib + (16 + s * 4 + a) * 1024 + lane * 16); S[a] = MFMA32(ka, vb[Q][s], S[a]); }
;     }
;     fetch_v(min(step + 2, s1 - 1), PP);
	v_pk_mul_f32 v[42:43], v[42:43], v[174:175]
	ds_bpermute_b32 v174, v143, v165
	ds_bpermute_b32 v176, v145, v165
	ds_bpermute_b32 v178, v147, v165
	ds_bpermute_b32 v180, v149, v165
	ds_bpermute_b32 v181, v150, v165
	ds_bpermute_b32 v179, v148, v165
	ds_bpermute_b32 v177, v146, v165
	ds_bpermute_b32 v175, v144, v165
	ds_read_b128 v[106:109], v171 offset:51200
	v_mfma_f32_32x32x16_bf16 v[34:49], v[110:113], v[94:97], v[34:49]
	ds_read_b128 v[110:113], v171 offset:52224
	s_waitcnt lgkmcnt(5)
	v_mul_f32_e64 v32, v32, v180
	v_mul_f32_e64 v33, v33, v181
	s_waitcnt lgkmcnt(4)
	v_pk_mul_f32 v[30:31], v[30:31], v[178:179]
	s_waitcnt lgkmcnt(3)
	v_pk_mul_f32 v[28:29], v[28:29], v[176:177]
	s_waitcnt lgkmcnt(2)
	v_pk_mul_f32 v[26:27], v[26:27], v[174:175]
	ds_bpermute_b32 v174, v151, v165
	ds_bpermute_b32 v175, v152, v165
	ds_bpermute_b32 v176, v153, v165
	ds_bpermute_b32 v177, v154, v165
	ds_bpermute_b32 v178, v155, v165
	ds_bpermute_b32 v179, v156, v165
	ds_bpermute_b32 v180, v157, v165
	ds_bpermute_b32 v181, v158, v165
	ds_bpermute_b32 v182, v159, v165
	ds_bpermute_b32 v183, v160, v165
	ds_bpermute_b32 v184, v166, v165
	ds_bpermute_b32 v185, v167, v165
	ds_bpermute_b32 v186, v161, v165
	ds_bpermute_b32 v188, v163, v165
	ds_bpermute_b32 v189, v164, v165
	ds_bpermute_b32 v187, v162, v165
	s_waitcnt lgkmcnt(4)
	v_pk_mul_f32 v[16:17], v[16:17], v[184:185]
	v_pk_mul_f32 v[10:11], v[10:11], v[182:183]
	v_pk_mul_f32 v[8:9], v[8:9], v[180:181]
	s_waitcnt lgkmcnt(1)
	v_pk_mul_f32 v[14:15], v[14:15], v[188:189]
	s_waitcnt lgkmcnt(0)
	v_pk_mul_f32 v[12:13], v[12:13], v[186:187]
	v_pk_mul_f32 v[6:7], v[6:7], v[178:179]
	v_pk_mul_f32 v[4:5], v[4:5], v[176:177]
	v_pk_mul_f32 v[2:3], v[2:3], v[174:175]
	v_mfma_f32_32x32x16_bf16 v[18:33], v[106:109], v[94:97], v[18:33]
	s_lshl_b64 s[20:21], s[20:21], 1
	s_or_b64 s[20:21], s[20:21], s[10:11]
	s_lshl_b64 s[34:35], s[20:21], 14
	s_add_u32 s34, s24, s34
	s_addc_u32 s35, s25, s35
	v_mov_b32_e32 v127, v115
	v_mov_b32_e32 v131, v115
	v_mfma_f32_32x32x16_bf16 v[2:17], v[110:113], v[94:97], v[2:17]
	ds_read_b128 v[94:97], v171 offset:53248
	ds_read_b128 v[106:109], v171 offset:54272
	v_mov_b32_e32 v129, v115
	s_lshl_b64 s[20:21], s[20:21], 9
	s_andn2_b64 vcc, exec, s[18:19]
	s_mov_b64 s[18:19], s[16:17]
	s_waitcnt lgkmcnt(1)
	v_mfma_f32_32x32x16_bf16 v[50:65], v[94:97], v[90:93], v[50:65]
	s_waitcnt lgkmcnt(0)
	v_mfma_f32_32x32x16_bf16 v[34:49], v[106:109], v[90:93], v[34:49]
	ds_read_b128 v[94:97], v171 offset:55296
	ds_read_b128 v[106:109], v171 offset:56320
	s_waitcnt lgkmcnt(1)
	v_mfma_f32_32x32x16_bf16 v[18:33], v[94:97], v[90:93], v[18:33]
	s_waitcnt lgkmcnt(0)
	v_mfma_f32_32x32x16_bf16 v[2:17], v[106:109], v[90:93], v[2:17]
	ds_read_b128 v[90:93], v171 offset:57344
	ds_read_b128 v[94:97], v171 offset:58368
	s_waitcnt lgkmcnt(1)
	v_mfma_f32_32x32x16_bf16 v[50:65], v[90:93], v[86:89], v[50:65]
	s_waitcnt lgkmcnt(0)
	v_mfma_f32_32x32x16_bf16 v[34:49], v[94:97], v[86:89], v[34:49]
	ds_read_b128 v[90:93], v171 offset:59392
	ds_read_b128 v[94:97], v171 offset:60416
	s_waitcnt lgkmcnt(1)
	v_mfma_f32_32x32x16_bf16 v[18:33], v[90:93], v[86:89], v[18:33]
	ds_read_b128 v[90:93], v171 offset:61440
	s_waitcnt lgkmcnt(1)
	v_mfma_f32_32x32x16_bf16 v[2:17], v[94:97], v[86:89], v[2:17]
	ds_read_b128 v[86:89], v171 offset:62464
	v_lshl_add_u64 v[94:95], s[34:35], 0, v[114:115]
	v_lshl_add_u64 v[96:97], s[34:35], 0, v[130:131]
	s_waitcnt lgkmcnt(1)
	v_mfma_f32_32x32x16_bf16 v[50:65], v[90:93], v[82:85], v[50:65]
	v_lshl_add_u64 v[90:91], v[94:95], 0, v[126:127]
	v_lshl_add_u64 v[94:95], v[90:91], 0, v[128:129]
	ds_read_b128 v[90:93], v171 offset:63488
	s_waitcnt lgkmcnt(1)
	v_mfma_f32_32x32x16_bf16 v[34:49], v[86:89], v[82:85], v[34:49]
	v_lshl_add_u64 v[86:87], v[96:97], 0, v[126:127]
	v_lshl_add_u64 v[86:87], v[86:87], 0, v[128:129]
	global_load_dwordx4 v[110:113], v[94:95], off
	global_load_dwordx4 v[106:109], v[86:87], off
	ds_read_b128 v[86:89], v171 offset:64512
	s_waitcnt lgkmcnt(1)
	v_mfma_f32_32x32x16_bf16 v[18:33], v[90:93], v[82:85], v[18:33]
	s_waitcnt lgkmcnt(0)
	v_mfma_f32_32x32x16_bf16 v[2:17], v[86:89], v[82:85], v[2:17]
	s_cbranch_vccnz .LBB0_315
	s_add_i32 s20, s22, -4
	s_sub_i32 s21, 0x103, s22
	s_and_b64 s[18:19], s[14:15], exec
	s_cselect_b32 s18, s20, s21
	s_add_i32 s18, s18, s28
	s_ashr_i32 s19, s18, 31
	s_lshl_b64 s[18:19], s[18:19], 2
	s_or_b64 s[18:19], s[18:19], s[6:7]
